# speedup vs baseline: 1.0374x; 1.0019x over previous
;     const int nblk = N / 32, kb = item / nblk, nb = item % nblk, k0 = 64 * kb, n0 = 32 * nb;
;     f32x4 tv[8];
; #pragma unroll
;     for (int i = 0; i < 8; ++i) tv[i] = *(const f32x4*)(W + (size_t)(k0 + 8 * i + (lane >> 3)) * N + n0 + 4 * (lane & 7));
; __global__ void __launch_bounds__(512, 2) fwd_megakernel(Args a) {
;     ...
;         for (int it = gw; it < I_IN + 64; it += NGW) {
;             if (it < I_IN) { const int n0 = 32 * (it % (L0N / 32));
;                 if (n0 >= 3072 && n0 < 3200) transpose_item(ab_w_in, DM, L0N, (u16*)(ws + WS_WX_T), scr, it, lane, -3072);
;                 else transpose_item(ab_w_in, DM, L0N, (u16*)(ws + WS_WIN_T), scr, it, lane, n0 >= 3200 ? -128 : 0); }
;             else if (it < I_IN + 32) transpose_item(w_up, LORA, RW, (u16*)(ws + WS_WUP_T), scr, it - I_IN, lane);
;             else transpose_item(a_up, LORA, RW, (u16*)(ws + WS_AUP_T), scr, it - I_IN - 32, lane);
;         }
.LBB0_5:
	s_or_b64 exec, exec, s[4:5]
	s_load_dwordx16 s[40:55], s[0:1], 0x0
	s_lshr_b32 s3, s96, 6
	s_lshl_b32 s2, s97, 3
	s_add_i32 s92, s3, s2
	s_lshl_b32 s2, s3, 14
	s_lshl_b32 s94, s90, 3
	s_add_i32 s2, s2, 0
	v_and_b32_e32 v225, 63, v218
	v_writelane_b32 v252, s3, 14
	s_cmpk_gt_i32 s92, 0x20bf
	v_lshlrev_b32_e32 v18, 4, v218
	v_lshlrev_b32_e32 v166, 3, v218
	v_writelane_b32 v252, s2, 15
	s_cbranch_scc1 .LBB0_19
	v_lshrrev_b32_e32 v1, 3, v225
	v_and_b32_e32 v2, 7, v225
	v_readlane_b32 s16, v252, 15
	v_lshlrev_b32_e32 v2, 4, v2
	v_mul_u32_u24_e32 v3, 0x84, v1
	v_lshlrev_b32_e32 v4, 2, v1
	v_add_u32_e32 v3, v3, v2
	v_mul_u32_u24_e32 v5, 0x42, v2
	v_add_u32_e32 v4, v5, v4
	v_add_u32_e32 v3, s16, v3
	v_add_u32_e32 v4, s16, v4
	s_mov_b32 s12, s92
	s_waitcnt lgkmcnt(0)
	s_cmpk_lt_u32 s12, 0x2080
	s_cbranch_scc0 .Lp0tr_pa_lora
	s_mul_i32 s2, s12, 0x3f04
	s_lshr_b32 s2, s2, 22
	s_mul_i32 s3, s2, 0x104
	s_sub_u32 s3, s12, s3
	s_mul_i32 s8, s2, 0x208000
	s_lshl_b32 s9, s3, 7
	s_add_u32 s8, s8, s9
	s_add_u32 s8, s46, s8
	s_addc_u32 s9, s47, 0
	s_mov_b32 s15, 0x8200
	s_movk_i32 s13, 0x1000
	s_lshl_b32 s2, s2, 7
	s_sub_u32 vcc_lo, s3, 0x60
	s_cmp_lt_u32 vcc_lo, 4
	s_cbranch_scc0 .Lp0tr_pa_win
	s_lshl_b32 s3, vcc_lo, 17
	s_add_u32 s3, s3, s2
	s_add_u32 s4, s88, 0xff80000
	s_addc_u32 s5, s89, 0
	s_branch .Lp0tr_pa_dstadd
.Lp0tr_pa_win:
	s_cmp_gt_u32 s3, 0x63
	s_cselect_b32 vcc_lo, 4, 0
	s_sub_u32 s3, s3, vcc_lo
	s_lshl_b32 s3, s3, 17
	s_add_u32 s3, s3, s2
	s_add_u32 s4, s88, 0x200000
	s_addc_u32 s5, s89, 0
	s_branch .Lp0tr_pa_dstadd
.Lp0tr_pa_lora:
	s_sub_u32 s2, s12, 0x2080
	s_movk_i32 s15, 0x1000
	s_movk_i32 s13, 0x80
	s_cmp_lt_u32 s2, 32
	s_cbranch_scc0 .Lp0tr_pa_aup
	s_lshl_b32 s3, s2, 7
	s_add_u32 s8, s50, s3
	s_addc_u32 s9, s51, 0
	s_lshl_b32 s3, s2, 12
	s_add_u32 s4, s88, 0x110000
	s_addc_u32 s5, s89, 0
	s_branch .Lp0tr_pa_dstadd
.Lp0tr_pa_aup:
	s_sub_u32 s2, s2, 32
	s_lshl_b32 s3, s2, 7
	s_add_u32 s8, s54, s3
	s_addc_u32 s9, s55, 0
	s_lshl_b32 s3, s2, 12
	s_add_u32 s4, s88, 0x130000
	s_addc_u32 s5, s89, 0
.Lp0tr_pa_dstadd:
	s_add_u32 s4, s4, s3
	s_addc_u32 s5, s5, 0
	v_mad_u32_u24 v5, v1, s15, v2
	v_mad_u32_u24 v6, v1, s13, v2
	s_lshl_b32 s15, s15, 3
	global_load_dwordx4 v[8:11], v5, s[8:9]
	s_add_u32 s8, s8, s15
	s_addc_u32 s9, s9, 0
	global_load_dwordx4 v[12:15], v5, s[8:9]
	s_add_u32 s8, s8, s15
	s_addc_u32 s9, s9, 0
	global_load_dwordx4 v[20:23], v5, s[8:9]
	s_add_u32 s8, s8, s15
	s_addc_u32 s9, s9, 0
	global_load_dwordx4 v[24:27], v5, s[8:9]
	s_add_u32 s8, s8, s15
	s_addc_u32 s9, s9, 0
	global_load_dwordx4 v[28:31], v5, s[8:9]
	s_add_u32 s8, s8, s15
	s_addc_u32 s9, s9, 0
	global_load_dwordx4 v[32:35], v5, s[8:9]
	s_add_u32 s8, s8, s15
	s_addc_u32 s9, s9, 0
	global_load_dwordx4 v[36:39], v5, s[8:9]
	s_add_u32 s8, s8, s15
	s_addc_u32 s9, s9, 0
	global_load_dwordx4 v[40:43], v5, s[8:9]
.Lp0tr_loop:
	s_add_i32 s12, s12, s94
	s_cmpk_lt_u32 s12, 0x20c0
	s_cbranch_scc0 .Lp0tr_lastA
	s_cmpk_lt_u32 s12, 0x2080
	s_cbranch_scc0 .Lp0tr_lb_lora
	s_mul_i32 s2, s12, 0x3f04
	s_lshr_b32 s2, s2, 22
	s_mul_i32 s3, s2, 0x104
	s_sub_u32 s3, s12, s3
	s_mul_i32 s8, s2, 0x208000
	s_lshl_b32 s9, s3, 7
	s_add_u32 s8, s8, s9
	s_add_u32 s8, s46, s8
	s_addc_u32 s9, s47, 0
	s_mov_b32 s15, 0x8200
	s_movk_i32 s14, 0x1000
	s_lshl_b32 s2, s2, 7
	s_sub_u32 vcc_lo, s3, 0x60
	s_cmp_lt_u32 vcc_lo, 4
	s_cbranch_scc0 .Lp0tr_lb_win
	s_lshl_b32 s3, vcc_lo, 17
	s_add_u32 s3, s3, s2
	s_add_u32 s6, s88, 0xff80000
	s_addc_u32 s7, s89, 0
	s_branch .Lp0tr_lb_dstadd
.Lp0tr_lb_win:
	s_cmp_gt_u32 s3, 0x63
	s_cselect_b32 vcc_lo, 4, 0
	s_sub_u32 s3, s3, vcc_lo
	s_lshl_b32 s3, s3, 17
	s_add_u32 s3, s3, s2
	s_add_u32 s6, s88, 0x200000
	s_addc_u32 s7, s89, 0
	s_branch .Lp0tr_lb_dstadd
.Lp0tr_lb_lora:
	s_sub_u32 s2, s12, 0x2080
	s_movk_i32 s15, 0x1000
	s_movk_i32 s14, 0x80
	s_cmp_lt_u32 s2, 32
	s_cbranch_scc0 .Lp0tr_lb_aup
	s_lshl_b32 s3, s2, 7
	s_add_u32 s8, s50, s3
	s_addc_u32 s9, s51, 0
	s_lshl_b32 s3, s2, 12
	s_add_u32 s6, s88, 0x110000
	s_addc_u32 s7, s89, 0
	s_branch .Lp0tr_lb_dstadd
.Lp0tr_lb_aup:
	s_sub_u32 s2, s2, 32
	s_lshl_b32 s3, s2, 7
	s_add_u32 s8, s54, s3
	s_addc_u32 s9, s55, 0
	s_lshl_b32 s3, s2, 12
	s_add_u32 s6, s88, 0x130000
	s_addc_u32 s7, s89, 0
; #define LAS __attribute__((address_space(3)))
; DI unsigned pk2(float lo, float hi) { const f32x2 v = {lo, hi}; const bf16x2_t b = __builtin_convertvector(v, bf16x2_t); return __builtin_bit_cast(unsigned, b); }
; #define LDS_WAIT() asm volatile("s_waitcnt lgkmcnt(0)" ::: "memory")
;     const int nblk = N / 32, kb = item / nblk, nb = item % nblk, k0 = 64 * kb, n0 = 32 * nb;
;     f32x4 tv[8];
; #pragma unroll
;     for (int i = 0; i < 8; ++i) tv[i] = *(const f32x4*)(W + (size_t)(k0 + 8 * i + (lane >> 3)) * N + n0 + 4 * (lane & 7));
; #pragma unroll
;     for (int i = 0; i < 8; ++i) { LAS float* d = scr + (8 * i + (lane >> 3)) * 33 + 4 * (lane & 7); d[0] = tv[i].x; d[1] = tv[i].y; d[2] = tv[i].z; d[3] = tv[i].w; }
;     LDS_WAIT();
;     const int c = lane & 7;
; #pragma unroll
;     for (int j = 0; j < 4; ++j) { const int n = (lane >> 3) + 8 * j; const LAS float* s = scr + (8 * c) * 33 + n;
;         u32x4 o; o.x = pk2(s[0 * 33], s[1 * 33]); o.y = pk2(s[2 * 33], s[3 * 33]); o.z = pk2(s[4 * 33], s[5 * 33]); o.w = pk2(s[6 * 33], s[7 * 33]);
;         *(u32x4*)(WT + (size_t)(row_off + n0 + n) * K + k0 + 8 * c) = o; }
;     LDS_WAIT();
; }
; __global__ void __launch_bounds__(512, 2) fwd_megakernel(Args a) {
;     ...
;         for (int it = gw; it < I_IN + 64; it += NGW) {
;             if (it < I_IN) { const int n0 = 32 * (it % (L0N / 32));
;                 if (n0 >= 3072 && n0 < 3200) transpose_item(ab_w_in, DM, L0N, (u16*)(ws + WS_WX_T), scr, it, lane, -3072);
;                 else transpose_item(ab_w_in, DM, L0N, (u16*)(ws + WS_WIN_T), scr, it, lane, n0 >= 3200 ? -128 : 0); }
;             else if (it < I_IN + 32) transpose_item(w_up, LORA, RW, (u16*)(ws + WS_WUP_T), scr, it - I_IN, lane);
;             else transpose_item(a_up, LORA, RW, (u16*)(ws + WS_AUP_T), scr, it - I_IN - 32, lane);
.Lp0tr_lb_dstadd:
	s_add_u32 s6, s6, s3
	s_addc_u32 s7, s7, 0
	v_mad_u32_u24 v5, v1, s15, v2
	v_mad_u32_u24 v7, v1, s14, v2
	s_lshl_b32 s15, s15, 3
	global_load_dwordx4 v[44:47], v5, s[8:9]
	s_add_u32 s8, s8, s15
	s_addc_u32 s9, s9, 0
	global_load_dwordx4 v[48:51], v5, s[8:9]
	s_add_u32 s8, s8, s15
	s_addc_u32 s9, s9, 0
	global_load_dwordx4 v[52:55], v5, s[8:9]
	s_add_u32 s8, s8, s15
	s_addc_u32 s9, s9, 0
	global_load_dwordx4 v[56:59], v5, s[8:9]
	s_add_u32 s8, s8, s15
	s_addc_u32 s9, s9, 0
	global_load_dwordx4 v[60:63], v5, s[8:9]
	s_add_u32 s8, s8, s15
	s_addc_u32 s9, s9, 0
	global_load_dwordx4 v[64:67], v5, s[8:9]
	s_add_u32 s8, s8, s15
	s_addc_u32 s9, s9, 0
	global_load_dwordx4 v[68:71], v5, s[8:9]
	s_add_u32 s8, s8, s15
	s_addc_u32 s9, s9, 0
	global_load_dwordx4 v[72:75], v5, s[8:9]
	s_waitcnt vmcnt(15)
	ds_write_b32 v3, v8 offset:0
	ds_write_b32 v3, v9 offset:4
	ds_write_b32 v3, v10 offset:8
	ds_write_b32 v3, v11 offset:12
	s_waitcnt vmcnt(14)
	ds_write_b32 v3, v12 offset:1056
	ds_write_b32 v3, v13 offset:1060
	ds_write_b32 v3, v14 offset:1064
	ds_write_b32 v3, v15 offset:1068
	s_waitcnt vmcnt(13)
	ds_write_b32 v3, v20 offset:2112
	ds_write_b32 v3, v21 offset:2116
	ds_write_b32 v3, v22 offset:2120
	ds_write_b32 v3, v23 offset:2124
	s_waitcnt vmcnt(12)
	ds_write_b32 v3, v24 offset:3168
	ds_write_b32 v3, v25 offset:3172
	ds_write_b32 v3, v26 offset:3176
	ds_write_b32 v3, v27 offset:3180
	s_waitcnt vmcnt(11)
	ds_write_b32 v3, v28 offset:4224
	ds_write_b32 v3, v29 offset:4228
	ds_write_b32 v3, v30 offset:4232
	ds_write_b32 v3, v31 offset:4236
	s_waitcnt vmcnt(10)
	ds_write_b32 v3, v32 offset:5280
	ds_write_b32 v3, v33 offset:5284
	ds_write_b32 v3, v34 offset:5288
	ds_write_b32 v3, v35 offset:5292
	s_waitcnt vmcnt(9)
	ds_write_b32 v3, v36 offset:6336
	ds_write_b32 v3, v37 offset:6340
	ds_write_b32 v3, v38 offset:6344
	ds_write_b32 v3, v39 offset:6348
	s_waitcnt vmcnt(8)
	ds_write_b32 v3, v40 offset:7392
	ds_write_b32 v3, v41 offset:7396
	ds_write_b32 v3, v42 offset:7400
	ds_write_b32 v3, v43 offset:7404
	s_waitcnt lgkmcnt(0)
	ds_read2_b32 v[8:9], v4 offset0:0 offset1:33
	ds_read2_b32 v[10:11], v4 offset0:66 offset1:99
	ds_read2_b32 v[12:13], v4 offset0:132 offset1:165
	ds_read2_b32 v[14:15], v4 offset0:198 offset1:231
	ds_read2_b32 v[20:21], v4 offset0:8 offset1:41
	ds_read2_b32 v[22:23], v4 offset0:74 offset1:107
	ds_read2_b32 v[24:25], v4 offset0:140 offset1:173
	ds_read2_b32 v[26:27], v4 offset0:206 offset1:239
	ds_read2_b32 v[28:29], v4 offset0:16 offset1:49
	ds_read2_b32 v[30:31], v4 offset0:82 offset1:115
	ds_read2_b32 v[32:33], v4 offset0:148 offset1:181
	ds_read2_b32 v[34:35], v4 offset0:214 offset1:247
	ds_read2_b32 v[36:37], v4 offset0:24 offset1:57
	ds_read2_b32 v[38:39], v4 offset0:90 offset1:123
	ds_read2_b32 v[40:41], v4 offset0:156 offset1:189
	ds_read2_b32 v[42:43], v4 offset0:222 offset1:255
	s_lshl_b32 s2, s13, 3
	s_waitcnt lgkmcnt(12)
	v_cvt_pk_bf16_f32 v8, v8, v9
	v_cvt_pk_bf16_f32 v9, v10, v11
	v_cvt_pk_bf16_f32 v10, v12, v13
	v_cvt_pk_bf16_f32 v11, v14, v15
	global_store_dwordx4 v6, v[8:11], s[4:5]
	s_add_u32 s4, s4, s2
	s_addc_u32 s5, s5, 0
	s_waitcnt lgkmcnt(8)
	v_cvt_pk_bf16_f32 v20, v20, v21
	v_cvt_pk_bf16_f32 v21, v22, v23
	v_cvt_pk_bf16_f32 v22, v24, v25
	v_cvt_pk_bf16_f32 v23, v26, v27
	global_store_dwordx4 v6, v[20:23], s[4:5]
	s_add_u32 s4, s4, s2
	s_addc_u32 s5, s5, 0
	s_waitcnt lgkmcnt(4)
	v_cvt_pk_bf16_f32 v28, v28, v29
	v_cvt_pk_bf16_f32 v29, v30, v31
	v_cvt_pk_bf16_f32 v30, v32, v33
	v_cvt_pk_bf16_f32 v31, v34, v35
	global_store_dwordx4 v6, v[28:31], s[4:5]
	s_add_u32 s4, s4, s2
	s_addc_u32 s5, s5, 0
	s_waitcnt lgkmcnt(0)
	v_cvt_pk_bf16_f32 v36, v36, v37
	v_cvt_pk_bf16_f32 v37, v38, v39
	v_cvt_pk_bf16_f32 v38, v40, v41
	v_cvt_pk_bf16_f32 v39, v42, v43
	global_store_dwordx4 v6, v[36:39], s[4:5]
	s_add_i32 s12, s12, s94
	s_cmpk_lt_u32 s12, 0x20c0
	s_cbranch_scc0 .Lp0tr_lastB
	s_cmpk_lt_u32 s12, 0x2080
	s_cbranch_scc0 .Lp0tr_la_lora
	s_mul_i32 s2, s12, 0x3f04
	s_lshr_b32 s2, s2, 22
	s_mul_i32 s3, s2, 0x104
	s_sub_u32 s3, s12, s3
	s_mul_i32 s8, s2, 0x208000
	s_lshl_b32 s9, s3, 7
	s_add_u32 s8, s8, s9
	s_add_u32 s8, s46, s8
	s_addc_u32 s9, s47, 0
	s_mov_b32 s15, 0x8200
	s_movk_i32 s13, 0x1000
	s_lshl_b32 s2, s2, 7
	s_sub_u32 vcc_lo, s3, 0x60
	s_cmp_lt_u32 vcc_lo, 4
	s_cbranch_scc0 .Lp0tr_la_win
	s_lshl_b32 s3, vcc_lo, 17
	s_add_u32 s3, s3, s2
	s_add_u32 s4, s88, 0xff80000
	s_addc_u32 s5, s89, 0
	s_branch .Lp0tr_la_dstadd

; #define LAS __attribute__((address_space(3)))
; DI unsigned pk2(float lo, float hi) { const f32x2 v = {lo, hi}; const bf16x2_t b = __builtin_convertvector(v, bf16x2_t); return __builtin_bit_cast(unsigned, b); }
; #define LDS_WAIT() asm volatile("s_waitcnt lgkmcnt(0)" ::: "memory")
;     const int nblk = N / 32, kb = item / nblk, nb = item % nblk, k0 = 64 * kb, n0 = 32 * nb;
;     f32x4 tv[8];
; #pragma unroll
;     for (int i = 0; i < 8; ++i) tv[i] = *(const f32x4*)(W + (size_t)(k0 + 8 * i + (lane >> 3)) * N + n0 + 4 * (lane & 7));
; #pragma unroll
;     for (int i = 0; i < 8; ++i) { LAS float* d = scr + (8 * i + (lane >> 3)) * 33 + 4 * (lane & 7); d[0] = tv[i].x; d[1] = tv[i].y; d[2] = tv[i].z; d[3] = tv[i].w; }
;     LDS_WAIT();
;     const int c = lane & 7;
; #pragma unroll
;     for (int j = 0; j < 4; ++j) { const int n = (lane >> 3) + 8 * j; const LAS float* s = scr + (8 * c) * 33 + n;
;         u32x4 o; o.x = pk2(s[0 * 33], s[1 * 33]); o.y = pk2(s[2 * 33], s[3 * 33]); o.z = pk2(s[4 * 33], s[5 * 33]); o.w = pk2(s[6 * 33], s[7 * 33]);
;         *(u32x4*)(WT + (size_t)(row_off + n0 + n) * K + k0 + 8 * c) = o; }
;     LDS_WAIT();
.Lp0tr_la_dstadd:
	s_add_u32 s4, s4, s3
	s_addc_u32 s5, s5, 0
	v_mad_u32_u24 v5, v1, s15, v2
	v_mad_u32_u24 v6, v1, s13, v2
	s_lshl_b32 s15, s15, 3
	global_load_dwordx4 v[8:11], v5, s[8:9]
	s_add_u32 s8, s8, s15
	s_addc_u32 s9, s9, 0
	global_load_dwordx4 v[12:15], v5, s[8:9]
	s_add_u32 s8, s8, s15
	s_addc_u32 s9, s9, 0
	global_load_dwordx4 v[20:23], v5, s[8:9]
	s_add_u32 s8, s8, s15
	s_addc_u32 s9, s9, 0
	global_load_dwordx4 v[24:27], v5, s[8:9]
	s_add_u32 s8, s8, s15
	s_addc_u32 s9, s9, 0
	global_load_dwordx4 v[28:31], v5, s[8:9]
	s_add_u32 s8, s8, s15
	s_addc_u32 s9, s9, 0
	global_load_dwordx4 v[32:35], v5, s[8:9]
	s_add_u32 s8, s8, s15
	s_addc_u32 s9, s9, 0
	global_load_dwordx4 v[36:39], v5, s[8:9]
	s_add_u32 s8, s8, s15
	s_addc_u32 s9, s9, 0
	global_load_dwordx4 v[40:43], v5, s[8:9]
	s_waitcnt vmcnt(15)
	ds_write_b32 v3, v44 offset:0
	ds_write_b32 v3, v45 offset:4
	ds_write_b32 v3, v46 offset:8
	ds_write_b32 v3, v47 offset:12
	s_waitcnt vmcnt(14)
	ds_write_b32 v3, v48 offset:1056
	ds_write_b32 v3, v49 offset:1060
	ds_write_b32 v3, v50 offset:1064
	ds_write_b32 v3, v51 offset:1068
	s_waitcnt vmcnt(13)
	ds_write_b32 v3, v52 offset:2112
	ds_write_b32 v3, v53 offset:2116
	ds_write_b32 v3, v54 offset:2120
	ds_write_b32 v3, v55 offset:2124
	s_waitcnt vmcnt(12)
	ds_write_b32 v3, v56 offset:3168
	ds_write_b32 v3, v57 offset:3172
	ds_write_b32 v3, v58 offset:3176
	ds_write_b32 v3, v59 offset:3180
	s_waitcnt vmcnt(11)
	ds_write_b32 v3, v60 offset:4224
	ds_write_b32 v3, v61 offset:4228
	ds_write_b32 v3, v62 offset:4232
	ds_write_b32 v3, v63 offset:4236
	s_waitcnt vmcnt(10)
	ds_write_b32 v3, v64 offset:5280
	ds_write_b32 v3, v65 offset:5284
	ds_write_b32 v3, v66 offset:5288
	ds_write_b32 v3, v67 offset:5292
	s_waitcnt vmcnt(9)
	ds_write_b32 v3, v68 offset:6336
	ds_write_b32 v3, v69 offset:6340
	ds_write_b32 v3, v70 offset:6344
	ds_write_b32 v3, v71 offset:6348
	s_waitcnt vmcnt(8)
	ds_write_b32 v3, v72 offset:7392
	ds_write_b32 v3, v73 offset:7396
	ds_write_b32 v3, v74 offset:7400
	ds_write_b32 v3, v75 offset:7404
	s_waitcnt lgkmcnt(0)
	ds_read2_b32 v[44:45], v4 offset0:0 offset1:33
	ds_read2_b32 v[46:47], v4 offset0:66 offset1:99
	ds_read2_b32 v[48:49], v4 offset0:132 offset1:165
	ds_read2_b32 v[50:51], v4 offset0:198 offset1:231
	ds_read2_b32 v[52:53], v4 offset0:8 offset1:41
	ds_read2_b32 v[54:55], v4 offset0:74 offset1:107
	ds_read2_b32 v[56:57], v4 offset0:140 offset1:173
	ds_read2_b32 v[58:59], v4 offset0:206 offset1:239
	ds_read2_b32 v[60:61], v4 offset0:16 offset1:49
	ds_read2_b32 v[62:63], v4 offset0:82 offset1:115
	ds_read2_b32 v[64:65], v4 offset0:148 offset1:181
	ds_read2_b32 v[66:67], v4 offset0:214 offset1:247
	ds_read2_b32 v[68:69], v4 offset0:24 offset1:57
	ds_read2_b32 v[70:71], v4 offset0:90 offset1:123
	ds_read2_b32 v[72:73], v4 offset0:156 offset1:189
	ds_read2_b32 v[74:75], v4 offset0:222 offset1:255
	s_lshl_b32 s2, s14, 3
	s_waitcnt lgkmcnt(12)
	v_cvt_pk_bf16_f32 v44, v44, v45
	v_cvt_pk_bf16_f32 v45, v46, v47
	v_cvt_pk_bf16_f32 v46, v48, v49
	v_cvt_pk_bf16_f32 v47, v50, v51
	global_store_dwordx4 v7, v[44:47], s[6:7]
	s_add_u32 s6, s6, s2
	s_addc_u32 s7, s7, 0
	s_waitcnt lgkmcnt(8)
	v_cvt_pk_bf16_f32 v52, v52, v53
	v_cvt_pk_bf16_f32 v53, v54, v55
	v_cvt_pk_bf16_f32 v54, v56, v57
	v_cvt_pk_bf16_f32 v55, v58, v59
	global_store_dwordx4 v7, v[52:55], s[6:7]
	s_add_u32 s6, s6, s2
	s_addc_u32 s7, s7, 0
	s_waitcnt lgkmcnt(4)
	v_cvt_pk_bf16_f32 v60, v60, v61
	v_cvt_pk_bf16_f32 v61, v62, v63
	v_cvt_pk_bf16_f32 v62, v64, v65
	v_cvt_pk_bf16_f32 v63, v66, v67
	global_store_dwordx4 v7, v[60:63], s[6:7]
	s_add_u32 s6, s6, s2
	s_addc_u32 s7, s7, 0
	s_waitcnt lgkmcnt(0)
	v_cvt_pk_bf16_f32 v68, v68, v69
	v_cvt_pk_bf16_f32 v69, v70, v71
	v_cvt_pk_bf16_f32 v70, v72, v73
	v_cvt_pk_bf16_f32 v71, v74, v75
	global_store_dwordx4 v7, v[68:71], s[6:7]
	s_branch .Lp0tr_loop
; #define LAS __attribute__((address_space(3)))
; DI unsigned pk2(float lo, float hi) { const f32x2 v = {lo, hi}; const bf16x2_t b = __builtin_convertvector(v, bf16x2_t); return __builtin_bit_cast(unsigned, b); }
; #define LDS_WAIT() asm volatile("s_waitcnt lgkmcnt(0)" ::: "memory")
;     ...
; #pragma unroll
;     for (int i = 0; i < 8; ++i) { LAS float* d = scr + (8 * i + (lane >> 3)) * 33 + 4 * (lane & 7); d[0] = tv[i].x; d[1] = tv[i].y; d[2] = tv[i].z; d[3] = tv[i].w; }
;     LDS_WAIT();
;     const int c = lane & 7;
; #pragma unroll
;     for (int j = 0; j < 4; ++j) { const int n = (lane >> 3) + 8 * j; const LAS float* s = scr + (8 * c) * 33 + n;
;         u32x4 o; o.x = pk2(s[0 * 33], s[1 * 33]); o.y = pk2(s[2 * 33], s[3 * 33]); o.z = pk2(s[4 * 33], s[5 * 33]); o.w = pk2(s[6 * 33], s[7 * 33]);
;         *(u32x4*)(WT + (size_t)(row_off + n0 + n) * K + k0 + 8 * c) = o; }
;     LDS_WAIT();
.Lp0tr_lastA:
	s_waitcnt vmcnt(7)
	ds_write_b32 v3, v8 offset:0
	ds_write_b32 v3, v9 offset:4
	ds_write_b32 v3, v10 offset:8
	ds_write_b32 v3, v11 offset:12
	s_waitcnt vmcnt(6)
	ds_write_b32 v3, v12 offset:1056
	ds_write_b32 v3, v13 offset:1060
	ds_write_b32 v3, v14 offset:1064
	ds_write_b32 v3, v15 offset:1068
	s_waitcnt vmcnt(5)
	ds_write_b32 v3, v20 offset:2112
	ds_write_b32 v3, v21 offset:2116
	ds_write_b32 v3, v22 offset:2120
	ds_write_b32 v3, v23 offset:2124
	s_waitcnt vmcnt(4)
	ds_write_b32 v3, v24 offset:3168
	ds_write_b32 v3, v25 offset:3172
	ds_write_b32 v3, v26 offset:3176
	ds_write_b32 v3, v27 offset:3180
	s_waitcnt vmcnt(3)
	ds_write_b32 v3, v28 offset:4224
	ds_write_b32 v3, v29 offset:4228
	ds_write_b32 v3, v30 offset:4232
	ds_write_b32 v3, v31 offset:4236
	s_waitcnt vmcnt(2)
	ds_write_b32 v3, v32 offset:5280
	ds_write_b32 v3, v33 offset:5284
	ds_write_b32 v3, v34 offset:5288
	ds_write_b32 v3, v35 offset:5292
	s_waitcnt vmcnt(1)
	ds_write_b32 v3, v36 offset:6336
	ds_write_b32 v3, v37 offset:6340
	ds_write_b32 v3, v38 offset:6344
	ds_write_b32 v3, v39 offset:6348
	s_waitcnt vmcnt(0)
	ds_write_b32 v3, v40 offset:7392
	ds_write_b32 v3, v41 offset:7396
	ds_write_b32 v3, v42 offset:7400
	ds_write_b32 v3, v43 offset:7404
	s_waitcnt lgkmcnt(0)
	ds_read2_b32 v[8:9], v4 offset0:0 offset1:33
	ds_read2_b32 v[10:11], v4 offset0:66 offset1:99
	ds_read2_b32 v[12:13], v4 offset0:132 offset1:165
	ds_read2_b32 v[14:15], v4 offset0:198 offset1:231
	ds_read2_b32 v[20:21], v4 offset0:8 offset1:41
	ds_read2_b32 v[22:23], v4 offset0:74 offset1:107
	ds_read2_b32 v[24:25], v4 offset0:140 offset1:173
	ds_read2_b32 v[26:27], v4 offset0:206 offset1:239
	ds_read2_b32 v[28:29], v4 offset0:16 offset1:49
	ds_read2_b32 v[30:31], v4 offset0:82 offset1:115
	ds_read2_b32 v[32:33], v4 offset0:148 offset1:181
	ds_read2_b32 v[34:35], v4 offset0:214 offset1:247
	ds_read2_b32 v[36:37], v4 offset0:24 offset1:57
	ds_read2_b32 v[38:39], v4 offset0:90 offset1:123
	ds_read2_b32 v[40:41], v4 offset0:156 offset1:189
	ds_read2_b32 v[42:43], v4 offset0:222 offset1:255
	s_lshl_b32 s2, s13, 3
	s_waitcnt lgkmcnt(12)
	v_cvt_pk_bf16_f32 v8, v8, v9
	v_cvt_pk_bf16_f32 v9, v10, v11
	v_cvt_pk_bf16_f32 v10, v12, v13
	v_cvt_pk_bf16_f32 v11, v14, v15
	global_store_dwordx4 v6, v[8:11], s[4:5]
	s_add_u32 s4, s4, s2
	s_addc_u32 s5, s5, 0
	s_waitcnt lgkmcnt(8)
	v_cvt_pk_bf16_f32 v20, v20, v21
	v_cvt_pk_bf16_f32 v21, v22, v23
	v_cvt_pk_bf16_f32 v22, v24, v25
	v_cvt_pk_bf16_f32 v23, v26, v27
	global_store_dwordx4 v6, v[20:23], s[4:5]
	s_add_u32 s4, s4, s2
	s_addc_u32 s5, s5, 0
	s_waitcnt lgkmcnt(4)
	v_cvt_pk_bf16_f32 v28, v28, v29
	v_cvt_pk_bf16_f32 v29, v30, v31
	v_cvt_pk_bf16_f32 v30, v32, v33
	v_cvt_pk_bf16_f32 v31, v34, v35
	global_store_dwordx4 v6, v[28:31], s[4:5]
	s_add_u32 s4, s4, s2
	s_addc_u32 s5, s5, 0
	s_waitcnt lgkmcnt(0)
	v_cvt_pk_bf16_f32 v36, v36, v37
	v_cvt_pk_bf16_f32 v37, v38, v39
	v_cvt_pk_bf16_f32 v38, v40, v41
	v_cvt_pk_bf16_f32 v39, v42, v43
	global_store_dwordx4 v6, v[36:39], s[4:5]
	s_branch .LBB0_19
.Lp0tr_lastB:
	s_waitcnt vmcnt(7)
	ds_write_b32 v3, v44 offset:0
	ds_write_b32 v3, v45 offset:4
	ds_write_b32 v3, v46 offset:8
	ds_write_b32 v3, v47 offset:12
	s_waitcnt vmcnt(6)
	ds_write_b32 v3, v48 offset:1056
	ds_write_b32 v3, v49 offset:1060
	ds_write_b32 v3, v50 offset:1064
	ds_write_b32 v3, v51 offset:1068
	s_waitcnt vmcnt(5)
	ds_write_b32 v3, v52 offset:2112
	ds_write_b32 v3, v53 offset:2116
	ds_write_b32 v3, v54 offset:2120
	ds_write_b32 v3, v55 offset:2124
	s_waitcnt vmcnt(4)
	ds_write_b32 v3, v56 offset:3168
	ds_write_b32 v3, v57 offset:3172
	ds_write_b32 v3, v58 offset:3176
	ds_write_b32 v3, v59 offset:3180
	s_waitcnt vmcnt(3)
	ds_write_b32 v3, v60 offset:4224
	ds_write_b32 v3, v61 offset:4228
	ds_write_b32 v3, v62 offset:4232
	ds_write_b32 v3, v63 offset:4236
	s_waitcnt vmcnt(2)
	ds_write_b32 v3, v64 offset:5280
	ds_write_b32 v3, v65 offset:5284
	ds_write_b32 v3, v66 offset:5288
	ds_write_b32 v3, v67 offset:5292
	s_waitcnt vmcnt(1)
	ds_write_b32 v3, v68 offset:6336
	ds_write_b32 v3, v69 offset:6340
	ds_write_b32 v3, v70 offset:6344
	ds_write_b32 v3, v71 offset:6348
	s_waitcnt vmcnt(0)
	ds_write_b32 v3, v72 offset:7392
	ds_write_b32 v3, v73 offset:7396
	ds_write_b32 v3, v74 offset:7400
	ds_write_b32 v3, v75 offset:7404
	s_waitcnt lgkmcnt(0)
	ds_read2_b32 v[44:45], v4 offset0:0 offset1:33
	ds_read2_b32 v[46:47], v4 offset0:66 offset1:99
	ds_read2_b32 v[48:49], v4 offset0:132 offset1:165
	ds_read2_b32 v[50:51], v4 offset0:198 offset1:231
	ds_read2_b32 v[52:53], v4 offset0:8 offset1:41
	ds_read2_b32 v[54:55], v4 offset0:74 offset1:107
	ds_read2_b32 v[56:57], v4 offset0:140 offset1:173
	ds_read2_b32 v[58:59], v4 offset0:206 offset1:239
	ds_read2_b32 v[60:61], v4 offset0:16 offset1:49
	ds_read2_b32 v[62:63], v4 offset0:82 offset1:115
	ds_read2_b32 v[64:65], v4 offset0:148 offset1:181
	ds_read2_b32 v[66:67], v4 offset0:214 offset1:247
	ds_read2_b32 v[68:69], v4 offset0:24 offset1:57
	ds_read2_b32 v[70:71], v4 offset0:90 offset1:123
	ds_read2_b32 v[72:73], v4 offset0:156 offset1:189
	ds_read2_b32 v[74:75], v4 offset0:222 offset1:255
	s_lshl_b32 s2, s14, 3
	s_waitcnt lgkmcnt(12)
	v_cvt_pk_bf16_f32 v44, v44, v45
	v_cvt_pk_bf16_f32 v45, v46, v47
	v_cvt_pk_bf16_f32 v46, v48, v49
	v_cvt_pk_bf16_f32 v47, v50, v51
	global_store_dwordx4 v7, v[44:47], s[6:7]
	s_add_u32 s6, s6, s2
	s_addc_u32 s7, s7, 0
	s_waitcnt lgkmcnt(8)
	v_cvt_pk_bf16_f32 v52, v52, v53
	v_cvt_pk_bf16_f32 v53, v54, v55
	v_cvt_pk_bf16_f32 v54, v56, v57
	v_cvt_pk_bf16_f32 v55, v58, v59
	global_store_dwordx4 v7, v[52:55], s[6:7]
	s_add_u32 s6, s6, s2
	s_addc_u32 s7, s7, 0
	s_waitcnt lgkmcnt(4)
	v_cvt_pk_bf16_f32 v60, v60, v61
	v_cvt_pk_bf16_f32 v61, v62, v63
	v_cvt_pk_bf16_f32 v62, v64, v65
	v_cvt_pk_bf16_f32 v63, v66, v67
	global_store_dwordx4 v7, v[60:63], s[6:7]
	s_add_u32 s6, s6, s2
	s_addc_u32 s7, s7, 0
	s_waitcnt lgkmcnt(0)
	v_cvt_pk_bf16_f32 v68, v68, v69
	v_cvt_pk_bf16_f32 v69, v70, v71
	v_cvt_pk_bf16_f32 v70, v72, v73
	v_cvt_pk_bf16_f32 v71, v74, v75
	global_store_dwordx4 v7, v[68:71], s[6:7]
